# speedup vs baseline: 1.0064x; 1.0001x over previous
; __device__ __forceinline__ int tidx() { int t = threadIdx.x; asm volatile("" : "+v"(t)); return t; }
; template <int NT, bool LOWREG = false>
; __device__ __forceinline__ void gemm_mainloop(const bh* __restrict__ A, long lda, const bh* __restrict__ B, long ldb, int K,
;                                               char* lds, f32x4 (&acc)[4][NT]) {
;     ...
;   const int tid = tidx(), lane = tid & 63, wid = tid >> 6, wr = wid >> 1, wc = wid & 1, fr = lane & 15, fq = lane >> 4;
;   const int srow = tid >> 3, scol = (tid & 7) * 8;
;   const bh* Ap = A + (long)srow * lda + scol;
;   const bh* Bp = B + (long)srow * ldb + scol;
;   bf16x8 ra[4], rb[NB];
;   const int nk = K >> 6;
; #pragma unroll
;   for (int i = 0; i < 4; ++i) ra[i] = *reinterpret_cast<const bf16x8*>(Ap + (long)(64 * i) * lda);
; #pragma unroll
;   for (int i = 0; i < NB; ++i) rb[i] = *reinterpret_cast<const bf16x8*>(Bp + (long)(64 * i) * ldb);
; #pragma unroll
;   for (int i = 0; i < 4; ++i) *reinterpret_cast<bf16x8*>(lds + (srow + 64 * i) * LROW + scol * 2) = ra[i];
; #pragma unroll
;   for (int i = 0; i < NB; ++i) *reinterpret_cast<bf16x8*>(lds + A_BYTES + (srow + 64 * i) * LROW + scol * 2) = rb[i];
;   __syncthreads();
;     ...
;   for (int tile = (t_first >= 0 ? t_first : (int)blockIdx.x); tile < tm_n * tn_n; tile += (t_first >= 0 ? t_stride : (int)gridDim.x)) {
;     const int tn = tile / tm_n, tm = tile - tn * tm_n;
;     f32x4 acc[4][NT];
; #pragma unroll
;     for (int m = 0; m < 4; ++m)
; #pragma unroll
;       for (int n = 0; n < NT; ++n) acc[m][n] = f32x4{0.f, 0.f, 0.f, 0.f};
;     gemm_mainloop<NT>(A + (long)tm * 256 * lda, lda, Bt + (long)tn * BN * ldb, ldb, K, lds, acc);
.LBB0_1130:
	s_ashr_i32 s2, s14, 31
	s_lshr_b32 s2, s2, 26
	s_add_i32 s3, s14, s2
	s_and_b32 s8, s3, 0xffffffc0
	s_sub_i32 s4, s14, s8
	s_ashr_i32 s5, s4, 31
	v_mov_b32_e32 v22, v188
	s_ashr_i32 s2, s3, 6
	s_lshl_b64 s[10:11], s[4:5], 19
	s_add_u32 s10, s38, s10
	v_ashrrev_i32_e32 v8, 3, v22
	v_ashrrev_i32_e32 v9, 31, v8
	s_addc_u32 s11, s39, s11
	v_lshlrev_b64 v[10:11], 11, v[8:9]
	v_lshlrev_b32_e32 v2, 4, v22
	s_ashr_i32 s3, s2, 31
	v_lshl_add_u64 v[0:1], s[10:11], 0, v[10:11]
	v_and_b32_e32 v176, 0x70, v2
	s_lshl_b64 s[16:17], s[2:3], 18
	s_waitcnt vmcnt(10)
	v_lshl_add_u64 v[16:17], v[0:1], 0, v[176:177]
	s_mov_b32 s5, 0x20000
	s_add_u32 s18, s12, s16
	v_add_co_u32_e32 v4, vcc, s5, v16
	s_addc_u32 s19, s13, s17
	s_nop 0
	v_addc_co_u32_e32 v5, vcc, 0, v17, vcc
	s_mov_b32 s9, 0x40000
	v_lshl_add_u64 v[20:21], s[18:19], 0, v[10:11]
	v_add_co_u32_e32 v12, vcc, s9, v16
	s_mov_b32 s9, 0x60000
	s_nop 0
	v_addc_co_u32_e32 v13, vcc, 0, v17, vcc
	v_lshl_add_u64 v[20:21], v[20:21], 0, v[176:177]
	global_load_dwordx4 v[0:3], v[16:17], off
	global_load_dwordx4 v[24:27], v[20:21], off
	v_add_co_u32_e32 v16, vcc, s9, v16
	global_load_dwordx4 v[4:7], v[4:5], off
	s_nop 0
	v_addc_co_u32_e32 v17, vcc, 0, v17, vcc
	v_add_co_u32_e32 v20, vcc, s5, v20
	global_load_dwordx4 v[12:15], v[12:13], off
	s_nop 0
	v_addc_co_u32_e32 v21, vcc, 0, v21, vcc
	global_load_dwordx4 v[16:19], v[16:17], off
	v_mul_lo_u32 v8, v8, s73
	global_load_dwordx4 v[32:35], v[20:21], off
	v_add3_u32 v94, 32, v176, v8
	v_and_b32_e32 v8, 15, v22
	v_lshrrev_b32_e32 v9, 1, v22
	s_mov_b32 s5, 0x7ffffc0
	v_and_or_b32 v8, v9, s5, v8
	v_mul_lo_u32 v95, v8, s73
	v_and_b32_e32 v8, 0x4f, v22
	v_mul_u32_u24_e32 v96, 0xa0, v8
	v_and_b32_e32 v8, 7, v22
	s_ashr_i32 s9, s8, 31
	v_lshl_or_b32 v10, v8, 4, v10
	s_lshl_b64 s[8:9], s[8:9], 19
	v_subrev_co_u32_e32 v8, vcc, s8, v10
	v_mov_b32_e32 v9, s9
	v_readlane_b32 s8, v253, 55
	v_subb_co_u32_e32 v9, vcc, v11, v9, vcc
	v_readlane_b32 s9, v253, 56
	s_add_u32 s8, s8, s16
	v_lshl_add_u64 v[88:89], s[0:1], 0, v[8:9]
	s_addc_u32 s9, s9, s17
	v_mov_b32_e32 v8, 0
	s_mov_b32 s3, 0
	v_and_b32_e32 v93, 48, v22
	v_lshl_add_u64 v[90:91], s[8:9], 0, v[10:11]
	s_mov_b64 s[8:9], 0
	v_mov_b32_e32 v9, v8
	v_mov_b32_e32 v10, v8
	v_mov_b32_e32 v11, v8
	v_mov_b32_e32 v20, v8
	v_mov_b32_e32 v21, v8
	v_mov_b32_e32 v22, v8
	v_mov_b32_e32 v23, v8
	v_mov_b32_e32 v28, v8
	v_mov_b32_e32 v29, v8
	v_mov_b32_e32 v30, v8
	v_mov_b32_e32 v31, v8
	v_mov_b32_e32 v36, v8
	v_mov_b32_e32 v37, v8
	v_mov_b32_e32 v38, v8
	v_mov_b32_e32 v39, v8
	s_waitcnt vmcnt(38)
	v_mov_b32_e32 v40, v8
	v_mov_b32_e32 v41, v8
	v_mov_b32_e32 v42, v8
	v_mov_b32_e32 v43, v8
	v_mov_b32_e32 v44, v8
	v_mov_b32_e32 v45, v8
	v_mov_b32_e32 v46, v8
	v_mov_b32_e32 v47, v8
	v_mov_b32_e32 v48, v8
	v_mov_b32_e32 v49, v8
	v_mov_b32_e32 v50, v8
	v_mov_b32_e32 v51, v8
	v_mov_b32_e32 v52, v8
	v_mov_b32_e32 v53, v8
	v_mov_b32_e32 v54, v8
	v_mov_b32_e32 v55, v8
	v_mov_b32_e32 v56, v8
	v_mov_b32_e32 v57, v8
	v_mov_b32_e32 v58, v8
	v_mov_b32_e32 v59, v8
	v_mov_b32_e32 v60, v8
	v_mov_b32_e32 v61, v8
	v_mov_b32_e32 v62, v8
	v_mov_b32_e32 v63, v8
	v_mov_b32_e32 v64, v8
	v_mov_b32_e32 v65, v8
	v_mov_b32_e32 v66, v8
	v_mov_b32_e32 v67, v8
	v_mov_b32_e32 v68, v8
	v_mov_b32_e32 v69, v8
	v_mov_b32_e32 v70, v8
	v_mov_b32_e32 v71, v8
	v_mov_b32_e32 v72, v8
	v_mov_b32_e32 v73, v8
	v_mov_b32_e32 v74, v8
	v_mov_b32_e32 v75, v8
	v_mov_b32_e32 v76, v8
	v_mov_b32_e32 v77, v8
	v_mov_b32_e32 v78, v8
	v_mov_b32_e32 v79, v8
	v_mov_b32_e32 v80, v8
	v_mov_b32_e32 v81, v8
	v_mov_b32_e32 v82, v8
	v_mov_b32_e32 v83, v8
	v_mov_b32_e32 v84, v8
	v_mov_b32_e32 v85, v8
	v_mov_b32_e32 v86, v8
	v_mov_b32_e32 v87, v8
	s_waitcnt vmcnt(5)
	ds_write_b128 v94, v[0:3]
	s_waitcnt vmcnt(3)
	ds_write_b128 v94, v[4:7] offset:10240
	s_waitcnt vmcnt(2)
	ds_write_b128 v94, v[12:15] offset:20480
	s_waitcnt vmcnt(1)
	ds_write_b128 v94, v[16:19] offset:30720
	ds_write_b128 v94, v[24:27] offset:40960
	s_waitcnt vmcnt(0)
	ds_write_b128 v94, v[32:35] offset:51200
	v_lshl_add_u64 v[12:13], v[88:89], 0, s[8:9]
	v_add_co_u32_e32 v0, vcc, 0x5770000, v12
	v_lshl_add_u64 v[24:25], v[90:91], 0, s[8:9]
	v_addc_co_u32_e32 v1, vcc, 0, v13, vcc
	v_add_co_u32_e32 v4, vcc, 0x5790000, v12
	s_nop 1
	v_addc_co_u32_e32 v5, vcc, 0, v13, vcc
	v_add_co_u32_e32 v14, vcc, 0x57b0000, v12
	global_load_dwordx4 v[0:3], v[0:1], off offset:128
	s_nop 0
	global_load_dwordx4 v[4:7], v[4:5], off offset:128
	v_addc_co_u32_e32 v15, vcc, 0, v13, vcc
	v_add_co_u32_e32 v16, vcc, 0x57d0000, v12
	s_nop 1
	v_addc_co_u32_e32 v17, vcc, 0, v13, vcc
	v_add_co_u32_e32 v26, vcc, 0x2538000, v24
	global_load_dwordx4 v[12:15], v[14:15], off offset:128
	s_nop 0
	global_load_dwordx4 v[16:19], v[16:17], off offset:128
	v_addc_co_u32_e32 v27, vcc, 0, v25, vcc
	v_add_co_u32_e32 v32, vcc, 0x2558000, v24
	s_nop 1
	v_addc_co_u32_e32 v33, vcc, 0, v25, vcc
	global_load_dwordx4 v[24:27], v[26:27], off offset:128
	s_nop 0
	global_load_dwordx4 v[32:35], v[32:33], off offset:128
	v_lshl_add_u64 v[140:141], v[88:89], 0, s[8:9]
	v_add_co_u32_e32 v132, vcc, 0x5770000, v140
	v_lshl_add_u64 v[148:149], v[90:91], 0, s[8:9]
	v_addc_co_u32_e32 v133, vcc, 0, v141, vcc
	v_add_co_u32_e32 v136, vcc, 0x5790000, v140
	s_nop 1
	v_addc_co_u32_e32 v137, vcc, 0, v141, vcc
	v_add_co_u32_e32 v142, vcc, 0x57b0000, v140
	global_load_dwordx4 v[132:135], v[132:133], off offset:256
	s_nop 0
	global_load_dwordx4 v[136:139], v[136:137], off offset:256
	v_addc_co_u32_e32 v143, vcc, 0, v141, vcc
	v_add_co_u32_e32 v144, vcc, 0x57d0000, v140
	s_nop 1
	v_addc_co_u32_e32 v145, vcc, 0, v141, vcc
	v_add_co_u32_e32 v150, vcc, 0x2538000, v148
	global_load_dwordx4 v[140:143], v[142:143], off offset:256
	s_nop 0
	global_load_dwordx4 v[144:147], v[144:145], off offset:256
	v_addc_co_u32_e32 v151, vcc, 0, v149, vcc
	v_add_co_u32_e32 v152, vcc, 0x2558000, v148
	s_nop 1
	v_addc_co_u32_e32 v153, vcc, 0, v149, vcc
	global_load_dwordx4 v[148:151], v[150:151], off offset:256
	s_nop 0
	global_load_dwordx4 v[152:155], v[152:153], off offset:256
	s_waitcnt lgkmcnt(0)
	s_barrier
	s_branch .LBB0_1132
; __device__ __forceinline__ f32x4 mfma16(bf16x8 a, bf16x8 b, f32x4 c) { return __builtin_amdgcn_mfma_f32_16x16x32_bf16(a, b, c, 0, 0, 0); }
; template <int NT, bool LOWREG = false>
; __device__ __forceinline__ void gemm_mainloop(const bh* __restrict__ A, long lda, const bh* __restrict__ B, long ldb, int K,
;                                               char* lds, f32x4 (&acc)[4][NT]) {
;     ...
;   for (int kt = 0; kt < nk; ++kt) {
;     const bool more = kt + 1 < nk;
;     if (more) {
; #pragma unroll
;       for (int i = 0; i < 4; ++i) ra[i] = *reinterpret_cast<const bf16x8*>(Ap + (long)(64 * i) * lda + (kt + 1) * 64);
; #pragma unroll
;       for (int i = 0; i < NB; ++i) rb[i] = *reinterpret_cast<const bf16x8*>(Bp + (long)(64 * i) * ldb + (kt + 1) * 64);
;     }
;     const char* sb = lds + (kt & 1) * STAGE;
;     const char* a_base = sb + (wr * 64 + fr) * LROW + fq * 16;
;     const char* b_base = sb + A_BYTES + (wc * (16 * NT) + fr) * LROW + fq * 16;
; #pragma unroll
;     for (int ks = 0; ks < 2; ++ks) {
;       if constexpr (LOWREG) {
;         bf16x8 bfr[NT];
; #pragma unroll
;         for (int n = 0; n < NT; ++n) bfr[n] = *reinterpret_cast<const bf16x8*>(b_base + n * 16 * LROW + ks * 64);
; #pragma unroll
;         for (int mp = 0; mp < 2; ++mp) {
;           bf16x8 af[2];
; #pragma unroll
;           for (int m = 0; m < 2; ++m) af[m] = *reinterpret_cast<const bf16x8*>(a_base + (mp * 2 + m) * 16 * LROW + ks * 64);
;           __builtin_amdgcn_s_setprio(1);
; #pragma unroll
;           for (int m = 0; m < 2; ++m)
; #pragma unroll
;             for (int n = 0; n < NT; ++n) acc[mp * 2 + m][n] = mfma16(af[m], bfr[n], acc[mp * 2 + m][n]);
;           __builtin_amdgcn_s_setprio(0);
;         }
;       } else {
;       bf16x8 af[4], bfr[NT];
; #pragma unroll
;       for (int m = 0; m < 4; ++m) af[m] = *reinterpret_cast<const bf16x8*>(a_base + m * 16 * LROW + ks * 64);
; #pragma unroll
;       for (int n = 0; n < NT; ++n) bfr[n] = *reinterpret_cast<const bf16x8*>(b_base + n * 16 * LROW + ks * 64);
;       __builtin_amdgcn_s_setprio(1);
; #pragma unroll
;       for (int m = 0; m < 4; ++m)
; #pragma unroll
;         for (int n = 0; n < NT; ++n) acc[m][n] = mfma16(af[m], bfr[n], acc[m][n]);
;       __builtin_amdgcn_s_setprio(0);
.LBB0_1131:
	s_add_u32 s8, s8, 0x80
	s_addc_u32 s9, s9, 0
	s_cmpk_ge_i32 s8, 0x700
	s_cbranch_scc1 .Lmy_2a_skipA_1131
	v_lshl_add_u64 v[12:13], v[88:89], 0, s[8:9]
	v_add_co_u32_e32 v0, vcc, 0x5770000, v12
	v_lshl_add_u64 v[24:25], v[90:91], 0, s[8:9]
	v_addc_co_u32_e32 v1, vcc, 0, v13, vcc
	v_add_co_u32_e32 v4, vcc, 0x5790000, v12
	s_nop 1
	v_addc_co_u32_e32 v5, vcc, 0, v13, vcc
	v_add_co_u32_e32 v14, vcc, 0x57b0000, v12
	global_load_dwordx4 v[0:3], v[0:1], off offset:256
	s_nop 0
	global_load_dwordx4 v[4:7], v[4:5], off offset:256
	v_addc_co_u32_e32 v15, vcc, 0, v13, vcc
	v_add_co_u32_e32 v16, vcc, 0x57d0000, v12
	s_nop 1
	v_addc_co_u32_e32 v17, vcc, 0, v13, vcc
	v_add_co_u32_e32 v26, vcc, 0x2538000, v24
	global_load_dwordx4 v[12:15], v[14:15], off offset:256
	s_nop 0
	global_load_dwordx4 v[16:19], v[16:17], off offset:256
	v_addc_co_u32_e32 v27, vcc, 0, v25, vcc
	v_add_co_u32_e32 v32, vcc, 0x2558000, v24
	s_nop 1
	v_addc_co_u32_e32 v33, vcc, 0, v25, vcc
	global_load_dwordx4 v[24:27], v[26:27], off offset:256
	s_nop 0
	global_load_dwordx4 v[32:35], v[32:33], off offset:256
.Lmy_2a_skipA_1131:
	s_mov_b32 s3, s5
	s_waitcnt lgkmcnt(0)
	s_barrier
	s_add_i32 s5, s3, 1
	s_bitcmp1_b32 s3, 0
	s_cselect_b32 s3, 0xf000, 0
	s_add_i32 s3, s3, 32
	v_add3_u32 v97, s3, v95, v93
	v_add3_u32 v130, s3, v96, v93
	ds_read_b128 v[98:101], v97
	ds_read_b128 v[102:105], v97 offset:2560
	ds_read_b128 v[106:109], v97 offset:5120
	ds_read_b128 v[110:113], v97 offset:7680
	ds_read_b128 v[114:117], v130 offset:40960
	ds_read_b128 v[118:121], v130 offset:43520
	ds_read_b128 v[122:125], v130 offset:46080
	ds_read_b128 v[126:129], v130 offset:48640
	s_setprio 1
	s_waitcnt lgkmcnt(3)
	v_mfma_f32_16x16x32_bf16 v[84:87], v[98:101], v[114:117], v[84:87]
	s_waitcnt lgkmcnt(2)
	v_mfma_f32_16x16x32_bf16 v[80:83], v[98:101], v[118:121], v[80:83]
	s_waitcnt lgkmcnt(1)
	v_mfma_f32_16x16x32_bf16 v[76:79], v[98:101], v[122:125], v[76:79]
	s_waitcnt lgkmcnt(0)
	v_mfma_f32_16x16x32_bf16 v[72:75], v[98:101], v[126:129], v[72:75]
	v_mfma_f32_16x16x32_bf16 v[68:71], v[102:105], v[114:117], v[68:71]
	v_mfma_f32_16x16x32_bf16 v[64:67], v[102:105], v[118:121], v[64:67]
	v_mfma_f32_16x16x32_bf16 v[60:63], v[102:105], v[122:125], v[60:63]
	v_mfma_f32_16x16x32_bf16 v[56:59], v[102:105], v[126:129], v[56:59]
	v_mfma_f32_16x16x32_bf16 v[52:55], v[106:109], v[114:117], v[52:55]
	v_mfma_f32_16x16x32_bf16 v[48:51], v[106:109], v[118:121], v[48:51]
	v_mfma_f32_16x16x32_bf16 v[44:47], v[106:109], v[122:125], v[44:47]
	v_mfma_f32_16x16x32_bf16 v[40:43], v[106:109], v[126:129], v[40:43]
	v_mfma_f32_16x16x32_bf16 v[36:39], v[110:113], v[114:117], v[36:39]
	v_mfma_f32_16x16x32_bf16 v[28:31], v[110:113], v[118:121], v[28:31]
	v_mfma_f32_16x16x32_bf16 v[20:23], v[110:113], v[122:125], v[20:23]
	v_mfma_f32_16x16x32_bf16 v[8:11], v[110:113], v[126:129], v[8:11]
	s_setprio 0
	ds_read_b128 v[98:101], v97 offset:64
	ds_read_b128 v[102:105], v97 offset:2624
	ds_read_b128 v[106:109], v97 offset:5184
	ds_read_b128 v[110:113], v97 offset:7744
	ds_read_b128 v[114:117], v130 offset:41024
	ds_read_b128 v[118:121], v130 offset:43584
	ds_read_b128 v[122:125], v130 offset:46144
	ds_read_b128 v[126:129], v130 offset:48704
	s_cmpk_eq_i32 s8, 0x780
	s_cbranch_scc1 .Lmy_2a_lastB_1131
	s_bitcmp1_b32 s5, 0
	s_cselect_b32 s3, 0xf000, 0
	s_setprio 1
	s_waitcnt lgkmcnt(3)
	v_mfma_f32_16x16x32_bf16 v[84:87], v[98:101], v[114:117], v[84:87]
	s_waitcnt lgkmcnt(2)
	v_mfma_f32_16x16x32_bf16 v[80:83], v[98:101], v[118:121], v[80:83]
	s_waitcnt lgkmcnt(1)
	v_mfma_f32_16x16x32_bf16 v[76:79], v[98:101], v[122:125], v[76:79]
	s_waitcnt lgkmcnt(0)
	v_mfma_f32_16x16x32_bf16 v[72:75], v[98:101], v[126:129], v[72:75]
	v_mfma_f32_16x16x32_bf16 v[68:71], v[102:105], v[114:117], v[68:71]
	v_add_u32_e32 v97, s3, v94
	s_waitcnt vmcnt(11)
	ds_write_b128 v97, v[132:135]
	v_mfma_f32_16x16x32_bf16 v[64:67], v[102:105], v[118:121], v[64:67]
	v_mfma_f32_16x16x32_bf16 v[60:63], v[102:105], v[122:125], v[60:63]
	s_waitcnt vmcnt(10)
	ds_write_b128 v97, v[136:139] offset:10240
	v_mfma_f32_16x16x32_bf16 v[56:59], v[102:105], v[126:129], v[56:59]
	v_mfma_f32_16x16x32_bf16 v[52:55], v[106:109], v[114:117], v[52:55]
	s_waitcnt vmcnt(9)
	ds_write_b128 v97, v[140:143] offset:20480
	v_mfma_f32_16x16x32_bf16 v[48:51], v[106:109], v[118:121], v[48:51]
	v_mfma_f32_16x16x32_bf16 v[44:47], v[106:109], v[122:125], v[44:47]
	s_waitcnt vmcnt(8)
	ds_write_b128 v97, v[144:147] offset:30720
	v_mfma_f32_16x16x32_bf16 v[40:43], v[106:109], v[126:129], v[40:43]
	v_mfma_f32_16x16x32_bf16 v[36:39], v[110:113], v[114:117], v[36:39]
	s_waitcnt vmcnt(7)
	ds_write_b128 v97, v[148:151] offset:40960
	v_mfma_f32_16x16x32_bf16 v[28:31], v[110:113], v[118:121], v[28:31]
	v_mfma_f32_16x16x32_bf16 v[20:23], v[110:113], v[122:125], v[20:23]
	s_waitcnt vmcnt(6)
	ds_write_b128 v97, v[152:155] offset:51200
	v_mfma_f32_16x16x32_bf16 v[8:11], v[110:113], v[126:129], v[8:11]
	s_setprio 0
	s_branch .Lmy_2a_latchB_1131

; template <int NT, bool LOWREG = false>
; __device__ __forceinline__ void gemm_mainloop(const bh* __restrict__ A, long lda, const bh* __restrict__ B, long ldb, int K,
;                                               char* lds, f32x4 (&acc)[4][NT]) {
;     ...
;     if (more) {
; #pragma unroll
;       for (int i = 0; i < 4; ++i) ra[i] = *reinterpret_cast<const bf16x8*>(Ap + (long)(64 * i) * lda + (kt + 1) * 64);
; #pragma unroll
;       for (int i = 0; i < NB; ++i) rb[i] = *reinterpret_cast<const bf16x8*>(Bp + (long)(64 * i) * ldb + (kt + 1) * 64);
;     }
.Lmy_2a_latchB_1131:
	s_add_u32 s8, s8, 0x80
	s_addc_u32 s9, s9, 0
	s_cmpk_ge_i32 s8, 0x700
	s_cbranch_scc1 .Lmy_2a_skipB_1131
	v_lshl_add_u64 v[140:141], v[88:89], 0, s[8:9]
	v_add_co_u32_e32 v132, vcc, 0x5770000, v140
	v_lshl_add_u64 v[148:149], v[90:91], 0, s[8:9]
	v_addc_co_u32_e32 v133, vcc, 0, v141, vcc
	v_add_co_u32_e32 v136, vcc, 0x5790000, v140
	s_nop 1
	v_addc_co_u32_e32 v137, vcc, 0, v141, vcc
	v_add_co_u32_e32 v142, vcc, 0x57b0000, v140
	global_load_dwordx4 v[132:135], v[132:133], off offset:256
	s_nop 0
	global_load_dwordx4 v[136:139], v[136:137], off offset:256
	v_addc_co_u32_e32 v143, vcc, 0, v141, vcc
	v_add_co_u32_e32 v144, vcc, 0x57d0000, v140
	s_nop 1
	v_addc_co_u32_e32 v145, vcc, 0, v141, vcc
	v_add_co_u32_e32 v150, vcc, 0x2538000, v148
	global_load_dwordx4 v[140:143], v[142:143], off offset:256
	s_nop 0
	global_load_dwordx4 v[144:147], v[144:145], off offset:256
	v_addc_co_u32_e32 v151, vcc, 0, v149, vcc
	v_add_co_u32_e32 v152, vcc, 0x2558000, v148
	s_nop 1
	v_addc_co_u32_e32 v153, vcc, 0, v149, vcc
	global_load_dwordx4 v[148:151], v[150:151], off offset:256
	s_nop 0
	global_load_dwordx4 v[152:155], v[152:153], off offset:256

; __device__ __forceinline__ f32x4 mfma16(bf16x8 a, bf16x8 b, f32x4 c) { return __builtin_amdgcn_mfma_f32_16x16x32_bf16(a, b, c, 0, 0, 0); }
; template <int NT, bool LOWREG = false>
; __device__ __forceinline__ void gemm_mainloop(const bh* __restrict__ A, long lda, const bh* __restrict__ B, long ldb, int K,
;                                               char* lds, f32x4 (&acc)[4][NT]) {
;     ...
;     const char* sb = lds + (kt & 1) * STAGE;
;     const char* a_base = sb + (wr * 64 + fr) * LROW + fq * 16;
;     const char* b_base = sb + A_BYTES + (wc * (16 * NT) + fr) * LROW + fq * 16;
; #pragma unroll
;     for (int ks = 0; ks < 2; ++ks) {
;       if constexpr (LOWREG) {
;         bf16x8 bfr[NT];
; #pragma unroll
;         for (int n = 0; n < NT; ++n) bfr[n] = *reinterpret_cast<const bf16x8*>(b_base + n * 16 * LROW + ks * 64);
; #pragma unroll
;         for (int mp = 0; mp < 2; ++mp) {
;           bf16x8 af[2];
; #pragma unroll
;           for (int m = 0; m < 2; ++m) af[m] = *reinterpret_cast<const bf16x8*>(a_base + (mp * 2 + m) * 16 * LROW + ks * 64);
;           __builtin_amdgcn_s_setprio(1);
; #pragma unroll
;           for (int m = 0; m < 2; ++m)
; #pragma unroll
;             for (int n = 0; n < NT; ++n) acc[mp * 2 + m][n] = mfma16(af[m], bfr[n], acc[mp * 2 + m][n]);
;           __builtin_amdgcn_s_setprio(0);
;         }
;       } else {
;       bf16x8 af[4], bfr[NT];
; #pragma unroll
;       for (int m = 0; m < 4; ++m) af[m] = *reinterpret_cast<const bf16x8*>(a_base + m * 16 * LROW + ks * 64);
; #pragma unroll
;       for (int n = 0; n < NT; ++n) bfr[n] = *reinterpret_cast<const bf16x8*>(b_base + n * 16 * LROW + ks * 64);
;       __builtin_amdgcn_s_setprio(1);
; #pragma unroll
;       for (int m = 0; m < 4; ++m)
; #pragma unroll
;         for (int n = 0; n < NT; ++n) acc[m][n] = mfma16(af[m], bfr[n], acc[m][n]);
;       __builtin_amdgcn_s_setprio(0);
;       }
;     }
;     if (more) {
;       char* wb = lds + ((kt + 1) & 1) * STAGE;
; #pragma unroll
;       for (int i = 0; i < 4; ++i) *reinterpret_cast<bf16x8*>(wb + (srow + 64 * i) * LROW + scol * 2) = ra[i];
; #pragma unroll
;       for (int i = 0; i < NB; ++i) *reinterpret_cast<bf16x8*>(wb + A_BYTES + (srow + 64 * i) * LROW + scol * 2) = rb[i];
;     }
;     __syncthreads();
.LBB0_1132:
	s_add_i32 s5, s3, 1
	s_bitcmp1_b32 s3, 0
	s_cselect_b32 s3, 0xf000, 0
	s_add_i32 s3, s3, 32
	v_add3_u32 v97, s3, v95, v93
	v_add3_u32 v130, s3, v96, v93
	ds_read_b128 v[98:101], v97
	ds_read_b128 v[102:105], v97 offset:2560
	ds_read_b128 v[106:109], v97 offset:5120
	ds_read_b128 v[110:113], v97 offset:7680
	ds_read_b128 v[114:117], v130 offset:40960
	ds_read_b128 v[118:121], v130 offset:43520
	ds_read_b128 v[122:125], v130 offset:46080
	ds_read_b128 v[126:129], v130 offset:48640
	s_setprio 1
	s_waitcnt lgkmcnt(3)
	v_mfma_f32_16x16x32_bf16 v[84:87], v[98:101], v[114:117], v[84:87]
	s_waitcnt lgkmcnt(2)
	v_mfma_f32_16x16x32_bf16 v[80:83], v[98:101], v[118:121], v[80:83]
	s_waitcnt lgkmcnt(1)
	v_mfma_f32_16x16x32_bf16 v[76:79], v[98:101], v[122:125], v[76:79]
	s_waitcnt lgkmcnt(0)
	v_mfma_f32_16x16x32_bf16 v[72:75], v[98:101], v[126:129], v[72:75]
	v_mfma_f32_16x16x32_bf16 v[68:71], v[102:105], v[114:117], v[68:71]
	v_mfma_f32_16x16x32_bf16 v[64:67], v[102:105], v[118:121], v[64:67]
	v_mfma_f32_16x16x32_bf16 v[60:63], v[102:105], v[122:125], v[60:63]
	v_mfma_f32_16x16x32_bf16 v[56:59], v[102:105], v[126:129], v[56:59]
	v_mfma_f32_16x16x32_bf16 v[52:55], v[106:109], v[114:117], v[52:55]
	v_mfma_f32_16x16x32_bf16 v[48:51], v[106:109], v[118:121], v[48:51]
	v_mfma_f32_16x16x32_bf16 v[44:47], v[106:109], v[122:125], v[44:47]
	v_mfma_f32_16x16x32_bf16 v[40:43], v[106:109], v[126:129], v[40:43]
	v_mfma_f32_16x16x32_bf16 v[36:39], v[110:113], v[114:117], v[36:39]
	v_mfma_f32_16x16x32_bf16 v[28:31], v[110:113], v[118:121], v[28:31]
	v_mfma_f32_16x16x32_bf16 v[20:23], v[110:113], v[122:125], v[20:23]
	v_mfma_f32_16x16x32_bf16 v[8:11], v[110:113], v[126:129], v[8:11]
	s_setprio 0
	ds_read_b128 v[98:101], v97 offset:64
	ds_read_b128 v[102:105], v97 offset:2624
	ds_read_b128 v[106:109], v97 offset:5184
	ds_read_b128 v[110:113], v97 offset:7744
	ds_read_b128 v[114:117], v130 offset:41024
	ds_read_b128 v[118:121], v130 offset:43584
	ds_read_b128 v[122:125], v130 offset:46144
	ds_read_b128 v[126:129], v130 offset:48704
	s_cmpk_eq_i32 s8, 0x700
	s_cbranch_scc1 .Lmy_2a_tailA_1131
	s_bitcmp1_b32 s5, 0
	s_cselect_b32 s3, 0xf000, 0
	s_setprio 1
	s_waitcnt lgkmcnt(3)
	v_mfma_f32_16x16x32_bf16 v[84:87], v[98:101], v[114:117], v[84:87]
	s_waitcnt lgkmcnt(2)
	v_mfma_f32_16x16x32_bf16 v[80:83], v[98:101], v[118:121], v[80:83]
	s_waitcnt lgkmcnt(1)
	v_mfma_f32_16x16x32_bf16 v[76:79], v[98:101], v[122:125], v[76:79]
	s_waitcnt lgkmcnt(0)
	v_mfma_f32_16x16x32_bf16 v[72:75], v[98:101], v[126:129], v[72:75]
	v_mfma_f32_16x16x32_bf16 v[68:71], v[102:105], v[114:117], v[68:71]
	v_add_u32_e32 v97, s3, v94
	s_waitcnt vmcnt(11)
	ds_write_b128 v97, v[0:3]
	v_mfma_f32_16x16x32_bf16 v[64:67], v[102:105], v[118:121], v[64:67]
	v_mfma_f32_16x16x32_bf16 v[60:63], v[102:105], v[122:125], v[60:63]
	s_waitcnt vmcnt(10)
	ds_write_b128 v97, v[4:7] offset:10240
	v_mfma_f32_16x16x32_bf16 v[56:59], v[102:105], v[126:129], v[56:59]
	v_mfma_f32_16x16x32_bf16 v[52:55], v[106:109], v[114:117], v[52:55]
	s_waitcnt vmcnt(9)
	ds_write_b128 v97, v[12:15] offset:20480
	v_mfma_f32_16x16x32_bf16 v[48:51], v[106:109], v[118:121], v[48:51]
	v_mfma_f32_16x16x32_bf16 v[44:47], v[106:109], v[122:125], v[44:47]
	s_waitcnt vmcnt(8)
	ds_write_b128 v97, v[16:19] offset:30720
	v_mfma_f32_16x16x32_bf16 v[40:43], v[106:109], v[126:129], v[40:43]
	v_mfma_f32_16x16x32_bf16 v[36:39], v[110:113], v[114:117], v[36:39]
	s_waitcnt vmcnt(7)
	ds_write_b128 v97, v[24:27] offset:40960
	v_mfma_f32_16x16x32_bf16 v[28:31], v[110:113], v[118:121], v[28:31]
	v_mfma_f32_16x16x32_bf16 v[20:23], v[110:113], v[122:125], v[20:23]
	s_waitcnt vmcnt(6)
	ds_write_b128 v97, v[32:35] offset:51200
	v_mfma_f32_16x16x32_bf16 v[8:11], v[110:113], v[126:129], v[8:11]
	s_setprio 0
	s_branch .LBB0_1131
.Lmy_2a_tailA_1131:
	s_bitcmp1_b32 s5, 0
	s_cselect_b32 s3, 0xf000, 0
	s_setprio 1
	s_waitcnt lgkmcnt(3)
	v_mfma_f32_16x16x32_bf16 v[84:87], v[98:101], v[114:117], v[84:87]
	s_waitcnt lgkmcnt(2)
	v_mfma_f32_16x16x32_bf16 v[80:83], v[98:101], v[118:121], v[80:83]
	s_waitcnt lgkmcnt(1)
	v_mfma_f32_16x16x32_bf16 v[76:79], v[98:101], v[122:125], v[76:79]
	s_waitcnt lgkmcnt(0)
	v_mfma_f32_16x16x32_bf16 v[72:75], v[98:101], v[126:129], v[72:75]
	v_mfma_f32_16x16x32_bf16 v[68:71], v[102:105], v[114:117], v[68:71]
	v_add_u32_e32 v97, s3, v94
	s_waitcnt vmcnt(5)
	ds_write_b128 v97, v[0:3]
	v_mfma_f32_16x16x32_bf16 v[64:67], v[102:105], v[118:121], v[64:67]
	v_mfma_f32_16x16x32_bf16 v[60:63], v[102:105], v[122:125], v[60:63]
	s_waitcnt vmcnt(4)
	ds_write_b128 v97, v[4:7] offset:10240
	v_mfma_f32_16x16x32_bf16 v[56:59], v[102:105], v[126:129], v[56:59]
	v_mfma_f32_16x16x32_bf16 v[52:55], v[106:109], v[114:117], v[52:55]
	s_waitcnt vmcnt(3)
	ds_write_b128 v97, v[12:15] offset:20480
	v_mfma_f32_16x16x32_bf16 v[48:51], v[106:109], v[118:121], v[48:51]
	v_mfma_f32_16x16x32_bf16 v[44:47], v[106:109], v[122:125], v[44:47]
	s_waitcnt vmcnt(2)
	ds_write_b128 v97, v[16:19] offset:30720
	v_mfma_f32_16x16x32_bf16 v[40:43], v[106:109], v[126:129], v[40:43]
	v_mfma_f32_16x16x32_bf16 v[36:39], v[110:113], v[114:117], v[36:39]
	s_waitcnt vmcnt(1)
	ds_write_b128 v97, v[24:27] offset:40960
	v_mfma_f32_16x16x32_bf16 v[28:31], v[110:113], v[118:121], v[28:31]
	v_mfma_f32_16x16x32_bf16 v[20:23], v[110:113], v[122:125], v[20:23]
	s_waitcnt vmcnt(0)
	ds_write_b128 v97, v[32:35] offset:51200
	v_mfma_f32_16x16x32_bf16 v[8:11], v[110:113], v[126:129], v[8:11]
	s_setprio 0
	s_branch .LBB0_1131
